# attention static priority raise on the other half (waves 0-3) instead of waves 4-7; otherwise v79
# baseline (speedup 1.0000x reference)
; #define LAS __attribute__((address_space(3)))
; __device__ __forceinline__ void attn_phase(const Args& a, int layer, LAS unsigned char* lds, int tid, int wave, int lane) {
;     unsigned char* cb = a.ws + WS_CR;
;     const bf16_t* QR = (const bf16_t*)(cb + C_QR); const bf16_t* KR = (const bf16_t*)(cb + C_KR); const bf16_t* VT = (const bf16_t*)(cb + C_VT); bf16_t* YS = (bf16_t*)(cb + C_YS);
;     const int half = lane >> 5, r31 = lane & 31;
;     const float sc2 = 0.08838834764831845f * LOG2E;
;     const int nunits = layer == 1 ? 1024 : 1024 + 32;
;     const int krow_s = tid >> 4, kc_s = tid & 15, vrow_s = tid >> 2, vc_s = tid & 3;
;     const int G_ = gridDim.x, nr = (1024 + G_ - 1) / G_;
;     for (int it = 0; ; ++it) {
;         int u;
;         if (it < nr) { u = blockIdx.x + it * G_; if (u >= 1024) continue; }
;         else { u = 1024 + (G_ - 1 - (int)blockIdx.x) + (it - nr) * G_; if (u >= nunits) break; }
;         int b, kvh, qb; bool isc;
;         if (u < 1024) { isc = false; b = u >> 8; kvh = (u >> 7) & 1; qb = u & 127; } else { const int uc = u - 1024; isc = true; b = uc >> 3; kvh = (uc >> 2) & 1; qb = uc & 3; }
;         const int th = wave & 1, g = wave >> 1, hq = kvh * 4 + g, t0 = qb * 64, tq0 = t0 + th * 32;
;         const int qrow0 = isc ? b * CTXL : MC + b * SEQ;
;         const int klo = isc ? 0 : (t0 >= 128 ? -4 : -(t0 >> 5)), khi = isc ? -1 : ((SEQ - t0) / 32 - 1 < 5 ? (SEQ - t0) / 32 - 1 : 5);
;         const int nloc = khi - klo + 1, nt = nloc + 8;
.LBB0_884:
	s_add_u32 s42, s50, 0x4de00000
	s_addc_u32 s43, s51, 0
	s_and_b64 s[2:3], s[84:85], exec
	s_movk_i32 s1, 0x420
	s_cselect_b32 s1, s1, 0x400
	s_abs_i32 s3, s60
	v_cvt_f32_u32_e32 v3, s3
	s_sub_i32 s8, 0, s3
	s_add_i32 s2, s60, 0x3ff
	s_abs_i32 s7, s2
	v_rcp_iflag_f32_e32 v3, v3
	s_xor_b32 s5, s2, s60
	s_ashr_i32 s5, s5, 31
	v_ashrrev_i32_e32 v2, 4, v131
	v_mul_f32_e32 v3, 0x4f7ffffe, v3
	v_cvt_u32_f32_e32 v3, v3
	v_readlane_b32 s12, v254, 42
	v_readlane_b32 s13, v254, 43
	v_lshlrev_b32_e32 v8, 4, v152
	v_readfirstlane_b32 s9, v3
	s_mul_i32 s8, s8, s9
	s_mul_hi_u32 s8, s9, s8
	s_add_i32 s9, s9, s8
	s_mul_hi_u32 s8, s7, s9
	s_mul_i32 s9, s8, s3
	s_sub_i32 s7, s7, s9
	s_add_i32 s9, s8, 1
	s_sub_i32 s11, s7, s3
	s_cmp_ge_u32 s7, s3
	s_cselect_b32 s8, s9, s8
	v_ashrrev_i32_e32 v3, 31, v2
	s_cselect_b32 s7, s11, s7
	s_add_i32 s9, s8, 1
	v_lshlrev_b64 v[6:7], 9, v[2:3]
	s_cmp_ge_u32 s7, s3
	v_lshl_add_u64 v[6:7], s[50:51], 0, v[6:7]
	v_mov_b32_e32 v9, v175
	s_cselect_b32 s3, s9, s8
	s_lshl_b32 s9, s12, 3
	v_lshl_add_u64 v[6:7], v[6:7], 0, v[8:9]
	s_mov_b64 s[12:13], 0x52000000
	v_and_b32_e32 v166, 48, v135
	v_mov_b32_e32 v167, v175
	v_lshl_add_u64 v[164:165], v[6:7], 0, s[12:13]
	v_lshl_add_u64 v[6:7], s[50:51], 0, v[166:167]
	s_mov_b64 s[12:13], 0x53080000
	s_xor_b32 s3, s3, s5
	v_lshl_add_u64 v[168:169], v[6:7], 0, s[12:13]
	s_movk_i32 s12, 0x110
	v_lshrrev_b32_e32 v5, 5, v171
	v_ashrrev_i32_e32 v162, 2, v131
	s_sub_i32 s3, s3, s5
	s_bfe_u32 s5, s20, 0x10006
	v_mul_lo_u32 v2, v2, s12
	s_movk_i32 s11, 0x48
	v_and_b32_e32 v177, 31, v131
	s_lshl_b32 s8, s5, 5
	v_lshlrev_b32_e32 v4, 3, v5
	v_cmp_gt_u32_e32 vcc, 32, v171
	v_add_u32_e32 v2, 0, v2
	v_mul_lo_u32 v3, v162, s11
	v_lshlrev_b32_e32 v170, 2, v5
	s_sub_i32 s11, s60, s96
	s_mov_b32 s2, 0
	s_ashr_i32 s7, s20, 7
	v_cndmask_b32_e64 v178, 0, 1.0, vcc
	v_ashrrev_i32_e32 v163, 31, v162
	v_add_u32_e32 v167, 0, v3
	v_add_u32_e32 v179, 0, v4
	v_lshlrev_b32_e32 v186, 4, v5
	v_mul_u32_u24_e32 v187, 0x48, v177
	v_mad_u32_u24 v188, v177, s12, 0
	v_or_b32_e32 v189, 1, v170
	v_or_b32_e32 v190, 2, v170
	v_or_b32_e32 v191, 3, v170
	v_or_b32_e32 v192, 8, v170
	v_or_b32_e32 v193, 9, v170
	v_or_b32_e32 v194, 10, v170
	v_or_b32_e32 v195, 11, v170
	v_or_b32_e32 v196, 16, v170
	v_or_b32_e32 v197, 17, v170
	v_or_b32_e32 v198, 18, v170
	v_or_b32_e32 v199, 19, v170
	v_or_b32_e32 v200, 24, v170
	v_or_b32_e32 v201, 25, v170
	v_or_b32_e32 v202, 26, v170
	v_or_b32_e32 v203, 27, v170
	s_addk_i32 s11, 0x3ff
	v_or_b32_e32 v204, s8, v177
	s_sub_i32 s12, 0, s5
	v_lshlrev_b32_e32 v174, 1, v4
	v_add_u32_e32 v205, v2, v8
	s_setprio 0
	v_readfirstlane_b32 s98, v0
	s_nop 3
	s_lshr_b32 s98, s98, 6
	s_cmp_ge_u32 s98, 4
	s_cbranch_scc1 .Lattn_prio_done
	s_setprio 1
